# v037 + attention-A K/V address math with 32-bit adds (no 64-bit mad) + packed f32 ops in window/cross attention unpacked to plain ops
# baseline (speedup 1.0000x reference)
.LBB0_497:
	s_add_i32 s11, s10, -1
	s_min_i32 s1, s11, s58
	s_mul_i32 s46, s1, 0xa0000
	s_lshl_b32 s44, s1, 7
	v_add_co_u32_e32 v200, vcc, s46, v194
	s_nop 1
	v_addc_co_u32_e32 v201, vcc, 0, v195, vcc
	v_add_co_u32_e32 v236, vcc, s44, v208
	s_nop 1
	v_addc_co_u32_e32 v237, vcc, 0, v209, vcc
	s_mov_b32 s12, s3
	s_mov_b32 s3, s0
	s_add_i32 s15, s12, 0
	s_add_i32 s24, s10, -2
	s_cmp_lt_u32 s24, s16
	s_cselect_b64 s[0:1], -1, 0
	s_add_i32 s23, s3, 0
	s_waitcnt lgkmcnt(0)
	s_barrier
	v_add_u32_e32 v252, s15, v193
	ds_read_b128 v[162:165], v252
	ds_read_b128 v[178:181], v252 offset:4608
	ds_read_b128 v[166:169], v252 offset:32
	ds_read_b128 v[182:185], v252 offset:4640
	ds_read_b128 v[170:173], v252 offset:64
	ds_read_b128 v[186:189], v252 offset:4672
	ds_read_b128 v[174:177], v252 offset:96
	ds_read_b128 v[82:85], v252 offset:4704
	global_load_dwordx4 v[154:157], v[200:201], off offset:1024
	global_load_dwordx4 v[158:161], v[236:237], off
	v_add_u32_e32 v253, s23, v0
	v_exp_f32_e32 v66, v66
	v_exp_f32_e32 v67, v67
	v_exp_f32_e32 v68, v68
	v_exp_f32_e32 v69, v69
	v_add_f32_e32 v246, v66, v67
	v_cvt_pk_bf16_f32 v66, v66, v67
	s_waitcnt lgkmcnt(7)
	v_mfma_f32_32x32x16_bf16 v[114:129], v[162:165], v[130:133], v[50:65]
	ds_read_b128 v[86:89], v253 offset:9216
	ds_read_b128 v[216:219], v253 offset:13824
	v_exp_f32_e32 v70, v70
	v_exp_f32_e32 v71, v71
	v_add_f32_e32 v246, v68, v246
	v_add_f32_e32 v246, v69, v246
	v_cvt_pk_bf16_f32 v67, v68, v69
	s_waitcnt lgkmcnt(8)
	v_mfma_f32_32x32x16_bf16 v[98:113], v[178:181], v[130:133], v[50:65]
	ds_read_b128 v[90:93], v253 offset:9248
	ds_read_b128 v[220:223], v253 offset:13856
	v_exp_f32_e32 v72, v72
	v_exp_f32_e32 v73, v73
	v_add_f32_e32 v246, v70, v246
	v_add_f32_e32 v246, v71, v246
	v_cvt_pk_bf16_f32 v68, v70, v71
	s_waitcnt lgkmcnt(9)
	v_mfma_f32_32x32x16_bf16 v[114:129], v[166:169], v[134:137], v[114:129]
	ds_read_b128 v[94:97], v253 offset:9280
	ds_read_b128 v[224:227], v253 offset:13888
	v_exp_f32_e32 v74, v74
	v_exp_f32_e32 v75, v75
	v_add_f32_e32 v246, v72, v246
	v_add_f32_e32 v246, v73, v246
	v_cvt_pk_bf16_f32 v69, v72, v73
	s_waitcnt lgkmcnt(10)
	v_mfma_f32_32x32x16_bf16 v[98:113], v[182:185], v[134:137], v[98:113]
	ds_read_b128 v[212:215], v253 offset:9312
	ds_read_b128 v[242:245], v253 offset:13920
	v_exp_f32_e32 v76, v76
	v_exp_f32_e32 v77, v77
	v_add_f32_e32 v246, v74, v246
	v_add_f32_e32 v246, v75, v246
	v_cvt_pk_bf16_f32 v70, v74, v75
	s_waitcnt lgkmcnt(11)
	v_mfma_f32_32x32x16_bf16 v[114:129], v[170:173], v[138:141], v[114:129]
	v_exp_f32_e32 v78, v78
	v_exp_f32_e32 v79, v79
	v_add_f32_e32 v246, v76, v246
	v_add_f32_e32 v246, v77, v246
	v_cvt_pk_bf16_f32 v71, v76, v77
	s_waitcnt lgkmcnt(10)
	v_mfma_f32_32x32x16_bf16 v[98:113], v[186:189], v[138:141], v[98:113]
	v_exp_f32_e32 v80, v80
	v_exp_f32_e32 v81, v81
	v_add_f32_e32 v246, v78, v246
	v_add_f32_e32 v246, v79, v246
	v_cvt_pk_bf16_f32 v72, v78, v79
	s_waitcnt lgkmcnt(9)
	v_mfma_f32_32x32x16_bf16 v[114:129], v[174:177], v[142:145], v[114:129]
	v_exp_f32_e32 v34, v34
	v_exp_f32_e32 v35, v35
	v_add_f32_e32 v246, v80, v246
	v_add_f32_e32 v246, v81, v246
	v_cvt_pk_bf16_f32 v73, v80, v81
	s_waitcnt lgkmcnt(8)
	v_mfma_f32_32x32x16_bf16 v[98:113], v[82:85], v[142:145], v[98:113]
	v_exp_f32_e32 v36, v36
	v_exp_f32_e32 v37, v37
	v_add_f32_e32 v247, v34, v35
	v_cvt_pk_bf16_f32 v74, v34, v35
	s_waitcnt lgkmcnt(7)
	v_mfma_f32_32x32x16_bf16 v[18:33], v[86:89], v[66:69], v[18:33]
	v_exp_f32_e32 v38, v38
	v_exp_f32_e32 v39, v39
	v_add_f32_e32 v247, v36, v247
	v_add_f32_e32 v247, v37, v247
	v_cvt_pk_bf16_f32 v75, v36, v37
	s_waitcnt lgkmcnt(6)
	v_mfma_f32_32x32x16_bf16 v[2:17], v[216:219], v[66:69], v[2:17]
	v_exp_f32_e32 v40, v40
	v_exp_f32_e32 v41, v41
	v_add_f32_e32 v247, v38, v247
	v_add_f32_e32 v247, v39, v247
	v_cvt_pk_bf16_f32 v76, v38, v39
	v_max3_f32 v248, v114, v115, v116
	s_waitcnt lgkmcnt(5)
	v_mfma_f32_32x32x16_bf16 v[18:33], v[90:93], v[70:73], v[18:33]
	v_exp_f32_e32 v42, v42
	v_exp_f32_e32 v43, v43
	v_add_f32_e32 v247, v40, v247
	v_add_f32_e32 v247, v41, v247
	v_cvt_pk_bf16_f32 v77, v40, v41
	v_max3_f32 v248, v248, v117, v118
	s_waitcnt lgkmcnt(4)
	v_mfma_f32_32x32x16_bf16 v[2:17], v[220:223], v[70:73], v[2:17]
	v_exp_f32_e32 v44, v44
	v_exp_f32_e32 v45, v45
	v_add_f32_e32 v247, v42, v247
	v_add_f32_e32 v247, v43, v247
	v_cvt_pk_bf16_f32 v78, v42, v43
	v_max3_f32 v248, v248, v119, v120
	v_max3_f32 v249, v98, v99, v100
	s_waitcnt lgkmcnt(3)
	v_mfma_f32_32x32x16_bf16 v[18:33], v[94:97], v[74:77], v[18:33]
	v_exp_f32_e32 v46, v46
	v_exp_f32_e32 v47, v47
	v_add_f32_e32 v247, v44, v247
	v_add_f32_e32 v247, v45, v247
	v_cvt_pk_bf16_f32 v79, v44, v45
	v_max3_f32 v248, v248, v121, v122
	v_max3_f32 v249, v249, v101, v102
	s_waitcnt lgkmcnt(2)
	v_mfma_f32_32x32x16_bf16 v[2:17], v[224:227], v[74:77], v[2:17]
	v_exp_f32_e32 v48, v48
	v_exp_f32_e32 v49, v49
	v_add_f32_e32 v247, v46, v247
	v_add_f32_e32 v247, v47, v247
	v_cvt_pk_bf16_f32 v80, v46, v47
	v_max3_f32 v248, v248, v123, v124
	v_max3_f32 v249, v249, v103, v104
	v_add_f32_e32 v247, v48, v247
	v_add_f32_e32 v247, v49, v247
	v_cvt_pk_bf16_f32 v81, v48, v49
	v_max3_f32 v248, v248, v125, v126
	v_max3_f32 v249, v249, v105, v106
	s_waitcnt lgkmcnt(1)
	v_mfma_f32_32x32x16_bf16 v[18:33], v[212:215], v[78:81], v[18:33]
	v_max3_f32 v248, v248, v127, v128
	v_max3_f32 v249, v249, v107, v108
	v_max_f32_e32 v248, v248, v129
	v_max3_f32 v249, v249, v109, v110
	v_max3_f32 v249, v249, v111, v112
	v_max_f32_e32 v249, v249, v113
	s_waitcnt lgkmcnt(0)
	v_mfma_f32_32x32x16_bf16 v[2:17], v[242:245], v[78:81], v[2:17]
	v_add_f32_e32 v210, v210, v246
	v_add_f32_e32 v210, v210, v247
	s_cmp_ge_u32 s24, s16
	s_cbranch_scc1 .Lattn_skipw1
	s_add_i32 s24, s2, 0
	v_add_u32_e32 v200, s24, v192
	v_add_u32_e32 v201, s24, v204
	s_waitcnt vmcnt(3)
	ds_write_b128 v200, v[146:149]
	s_waitcnt vmcnt(2)
	ds_write_b128 v201, v[150:153] offset:9216

.Lattn_cont_h1:
	s_min_i32 s24, s10, s58
	s_mul_i32 s46, s24, 0xa0000
	s_lshl_b32 s44, s24, 7
	v_add_co_u32_e32 v200, vcc, s46, v194
	s_nop 1
	v_addc_co_u32_e32 v201, vcc, 0, v195, vcc
	v_add_co_u32_e32 v236, vcc, s44, v208
	s_nop 1
	v_addc_co_u32_e32 v237, vcc, 0, v209, vcc
	s_waitcnt lgkmcnt(0)
	s_barrier
	v_add_u32_e32 v252, s2, v205
	ds_read_b128 v[162:165], v252
	ds_read_b128 v[178:181], v252 offset:4608
	ds_read_b128 v[166:169], v252 offset:32
	ds_read_b128 v[182:185], v252 offset:4640
	ds_read_b128 v[170:173], v252 offset:64
	ds_read_b128 v[186:189], v252 offset:4672
	ds_read_b128 v[174:177], v252 offset:96
	ds_read_b128 v[82:85], v252 offset:4704
	global_load_dwordx4 v[146:149], v[200:201], off offset:1024
	global_load_dwordx4 v[150:153], v[236:237], off
	v_add_u32_e32 v253, s15, v0
	v_exp_f32_e32 v114, v114
	v_exp_f32_e32 v115, v115
	v_exp_f32_e32 v116, v116
	v_exp_f32_e32 v117, v117
	v_add_f32_e32 v246, v114, v115
	v_cvt_pk_bf16_f32 v114, v114, v115
	s_waitcnt lgkmcnt(7)
	v_mfma_f32_32x32x16_bf16 v[66:81], v[162:165], v[130:133], v[50:65]
	ds_read_b128 v[86:89], v253 offset:9216
	ds_read_b128 v[216:219], v253 offset:13824
	v_exp_f32_e32 v118, v118
	v_exp_f32_e32 v119, v119
	v_add_f32_e32 v246, v116, v246
	v_add_f32_e32 v246, v117, v246
	v_cvt_pk_bf16_f32 v115, v116, v117
	s_waitcnt lgkmcnt(8)
	v_mfma_f32_32x32x16_bf16 v[34:49], v[178:181], v[130:133], v[50:65]
	ds_read_b128 v[90:93], v253 offset:9248
	ds_read_b128 v[220:223], v253 offset:13856
	v_exp_f32_e32 v120, v120
	v_exp_f32_e32 v121, v121
	v_add_f32_e32 v246, v118, v246
	v_add_f32_e32 v246, v119, v246
	v_cvt_pk_bf16_f32 v116, v118, v119
	s_waitcnt lgkmcnt(9)
	v_mfma_f32_32x32x16_bf16 v[66:81], v[166:169], v[134:137], v[66:81]
	ds_read_b128 v[94:97], v253 offset:9280
	ds_read_b128 v[224:227], v253 offset:13888
	v_exp_f32_e32 v122, v122
	v_exp_f32_e32 v123, v123
	v_add_f32_e32 v246, v120, v246
	v_add_f32_e32 v246, v121, v246
	v_cvt_pk_bf16_f32 v117, v120, v121
	s_waitcnt lgkmcnt(10)
	v_mfma_f32_32x32x16_bf16 v[34:49], v[182:185], v[134:137], v[34:49]
	ds_read_b128 v[212:215], v253 offset:9312
	ds_read_b128 v[242:245], v253 offset:13920
	v_exp_f32_e32 v124, v124
	v_exp_f32_e32 v125, v125
	v_add_f32_e32 v246, v122, v246
	v_add_f32_e32 v246, v123, v246
	v_cvt_pk_bf16_f32 v118, v122, v123
	s_waitcnt lgkmcnt(11)
	v_mfma_f32_32x32x16_bf16 v[66:81], v[170:173], v[138:141], v[66:81]
	v_exp_f32_e32 v126, v126
	v_exp_f32_e32 v127, v127
	v_add_f32_e32 v246, v124, v246
	v_add_f32_e32 v246, v125, v246
	v_cvt_pk_bf16_f32 v119, v124, v125
	s_waitcnt lgkmcnt(10)
	v_mfma_f32_32x32x16_bf16 v[34:49], v[186:189], v[138:141], v[34:49]
	v_exp_f32_e32 v128, v128
	v_exp_f32_e32 v129, v129
	v_add_f32_e32 v246, v126, v246
	v_add_f32_e32 v246, v127, v246
	v_cvt_pk_bf16_f32 v120, v126, v127
	s_waitcnt lgkmcnt(9)
	v_mfma_f32_32x32x16_bf16 v[66:81], v[174:177], v[142:145], v[66:81]
	v_exp_f32_e32 v98, v98
	v_exp_f32_e32 v99, v99
	v_add_f32_e32 v246, v128, v246
	v_add_f32_e32 v246, v129, v246
	v_cvt_pk_bf16_f32 v121, v128, v129
	s_waitcnt lgkmcnt(8)
	v_mfma_f32_32x32x16_bf16 v[34:49], v[82:85], v[142:145], v[34:49]
	v_exp_f32_e32 v100, v100
	v_exp_f32_e32 v101, v101
	v_add_f32_e32 v247, v98, v99
	v_cvt_pk_bf16_f32 v122, v98, v99
	s_waitcnt lgkmcnt(7)
	v_mfma_f32_32x32x16_bf16 v[18:33], v[86:89], v[114:117], v[18:33]
	v_exp_f32_e32 v102, v102
	v_exp_f32_e32 v103, v103
	v_add_f32_e32 v247, v100, v247
	v_add_f32_e32 v247, v101, v247
	v_cvt_pk_bf16_f32 v123, v100, v101
	s_waitcnt lgkmcnt(6)
	v_mfma_f32_32x32x16_bf16 v[2:17], v[216:219], v[114:117], v[2:17]
	v_exp_f32_e32 v104, v104
	v_exp_f32_e32 v105, v105
	v_add_f32_e32 v247, v102, v247
	v_add_f32_e32 v247, v103, v247
	v_cvt_pk_bf16_f32 v124, v102, v103
	v_max3_f32 v248, v66, v67, v68
	s_waitcnt lgkmcnt(5)
	v_mfma_f32_32x32x16_bf16 v[18:33], v[90:93], v[118:121], v[18:33]
	v_exp_f32_e32 v106, v106
	v_exp_f32_e32 v107, v107
	v_add_f32_e32 v247, v104, v247
	v_add_f32_e32 v247, v105, v247
	v_cvt_pk_bf16_f32 v125, v104, v105
	v_max3_f32 v248, v248, v69, v70
	s_waitcnt lgkmcnt(4)
	v_mfma_f32_32x32x16_bf16 v[2:17], v[220:223], v[118:121], v[2:17]
	v_exp_f32_e32 v108, v108
	v_exp_f32_e32 v109, v109
	v_add_f32_e32 v247, v106, v247
	v_add_f32_e32 v247, v107, v247
	v_cvt_pk_bf16_f32 v126, v106, v107
	v_max3_f32 v248, v248, v71, v72
	v_max3_f32 v249, v34, v35, v36
	s_waitcnt lgkmcnt(3)
	v_mfma_f32_32x32x16_bf16 v[18:33], v[94:97], v[122:125], v[18:33]
	v_exp_f32_e32 v110, v110
	v_exp_f32_e32 v111, v111
	v_add_f32_e32 v247, v108, v247
	v_add_f32_e32 v247, v109, v247
	v_cvt_pk_bf16_f32 v127, v108, v109
	v_max3_f32 v248, v248, v73, v74
	v_max3_f32 v249, v249, v37, v38
	s_waitcnt lgkmcnt(2)
	v_mfma_f32_32x32x16_bf16 v[2:17], v[224:227], v[122:125], v[2:17]
	v_exp_f32_e32 v112, v112
	v_exp_f32_e32 v113, v113
	v_add_f32_e32 v247, v110, v247
	v_add_f32_e32 v247, v111, v247
	v_cvt_pk_bf16_f32 v128, v110, v111
	v_max3_f32 v248, v248, v75, v76
	v_max3_f32 v249, v249, v39, v40
	v_add_f32_e32 v247, v112, v247
	v_add_f32_e32 v247, v113, v247
	v_cvt_pk_bf16_f32 v129, v112, v113
	v_max3_f32 v248, v248, v77, v78
	v_max3_f32 v249, v249, v41, v42
	s_waitcnt lgkmcnt(1)
	v_mfma_f32_32x32x16_bf16 v[18:33], v[212:215], v[126:129], v[18:33]
	v_max3_f32 v248, v248, v79, v80
	v_max3_f32 v249, v249, v43, v44
	v_max_f32_e32 v248, v248, v81
	v_max3_f32 v249, v249, v45, v46
	v_max3_f32 v249, v249, v47, v48
	v_max_f32_e32 v249, v249, v49
	s_waitcnt lgkmcnt(0)
	v_mfma_f32_32x32x16_bf16 v[2:17], v[242:245], v[126:129], v[2:17]
	v_add_f32_e32 v210, v210, v246
	v_add_f32_e32 v210, v210, v247
	s_cmp_ge_u32 s11, s16
	s_cbranch_scc1 .Lattn_skipw2
	v_add_u32_e32 v200, s23, v192
	v_add_u32_e32 v201, s23, v204
	s_waitcnt vmcnt(3)
	ds_write_b128 v200, v[154:157]
	s_waitcnt vmcnt(2)
	ds_write_b128 v201, v[158:161] offset:9216

; __device__ __forceinline__ unsigned pk2(float lo, float hi) { f32x2 v = {lo, hi}; bf16x2_t b = __builtin_convertvector(v, bf16x2_t); return __builtin_bit_cast(unsigned, b); }
; template <int HD, int MODE> ...
;     ...
;     float l_tot; { auto rr = __builtin_amdgcn_permlane32_swap(__float_as_uint(l_run), __float_as_uint(l_run), false, false); l_tot = __uint_as_float(rr[0]) + __uint_as_float(rr[1]); }
;     const float inv = 1.0f / l_tot;
;     gbf16* orow = Og + (size_t)(wid * 32 + r32) * o_pitch + 4 * hi;
; #pragma unroll
;     for (int d0 = 0; d0 < HD / 32; ++d0)
; #pragma unroll
;         for (int rq = 0; rq < 4; ++rq) { u32x2 w; w.x = pk2(o[d0][4 * rq] * inv, o[d0][4 * rq + 1] * inv); w.y = pk2(o[d0][4 * rq + 2] * inv, o[d0][4 * rq + 3] * inv);
;             *(gu32x2*)(orow + 32 * d0 + 8 * rq) = w; }
.LBB0_513:
	v_mov_b32_e32 v0, v101
	s_nop 1
	v_permlane32_swap_b32_e32 v101, v0
	v_add_f32_e32 v0, v101, v0
	v_div_scale_f32 v34, s[6:7], v0, v0, 1.0
	v_rcp_f32_e32 v35, v34
	s_lshl_b64 s[2:3], s[2:3], 10
	s_add_u32 s2, s23, s2
	s_addc_u32 s3, s24, s3
	v_fma_f32 v36, -v34, v35, 1.0
	v_fmac_f32_e32 v35, v36, v35
	v_div_scale_f32 v36, vcc, 1.0, v0, 1.0
	v_mul_f32_e32 v37, v36, v35
	v_fma_f32 v38, -v34, v37, v36
	v_fmac_f32_e32 v37, v38, v35
	v_fma_f32 v34, -v34, v37, v36
	v_ashrrev_i32_e32 v91, 31, v90
	s_add_u32 s2, s2, s4
	v_div_fmas_f32 v34, v34, v35, v37
	s_addc_u32 s3, s3, s5
	v_div_fixup_f32 v34, v34, v0, 1.0
	v_lshlrev_b64 v[36:37], 10, v[90:91]
	v_lshl_add_u64 v[36:37], s[2:3], 0, v[36:37]
	v_lshlrev_b32_e32 v0, 3, v98
	v_mul_f32_e32 v18, v18, v34
	v_mul_f32_e32 v19, v19, v34
	v_mul_f32_e32 v20, v20, v34
	v_mul_f32_e32 v21, v21, v34
	v_mul_f32_e32 v2, v2, v34
	v_mul_f32_e32 v3, v3, v34
	v_mul_f32_e32 v4, v4, v34
	v_mul_f32_e32 v5, v5, v34
	v_lshl_add_u64 v[36:37], v[36:37], 0, v[0:1]
	v_cvt_pk_bf16_f32 v18, v18, v19
	v_cvt_pk_bf16_f32 v19, v20, v21
	v_cvt_pk_bf16_f32 v2, v2, v3
	v_cvt_pk_bf16_f32 v3, v4, v5
	global_store_dwordx2 v[36:37], v[18:19], off
	v_mul_f32_e32 v18, v22, v34
	v_mul_f32_e32 v19, v23, v34
	v_mul_f32_e32 v20, v24, v34
	v_mul_f32_e32 v21, v25, v34
	global_store_dwordx2 v[36:37], v[2:3], off offset:64
	v_mul_f32_e32 v2, v6, v34
	v_mul_f32_e32 v3, v7, v34
	v_mul_f32_e32 v4, v8, v34
	v_mul_f32_e32 v5, v9, v34
	v_cvt_pk_bf16_f32 v18, v18, v19
	v_cvt_pk_bf16_f32 v19, v20, v21
	v_cvt_pk_bf16_f32 v2, v2, v3
	v_cvt_pk_bf16_f32 v3, v4, v5
	global_store_dwordx2 v[36:37], v[18:19], off offset:16
	v_mul_f32_e32 v18, v26, v34
	v_mul_f32_e32 v19, v27, v34
	v_mul_f32_e32 v20, v28, v34
	v_mul_f32_e32 v21, v29, v34
	global_store_dwordx2 v[36:37], v[2:3], off offset:80
	v_mul_f32_e32 v2, v10, v34
	v_mul_f32_e32 v3, v11, v34
	v_mul_f32_e32 v4, v12, v34
	v_mul_f32_e32 v5, v13, v34
	v_cvt_pk_bf16_f32 v18, v18, v19
	v_cvt_pk_bf16_f32 v19, v20, v21
	v_cvt_pk_bf16_f32 v2, v2, v3
	v_cvt_pk_bf16_f32 v3, v4, v5
	global_store_dwordx2 v[36:37], v[18:19], off offset:32
	v_mul_f32_e32 v18, v30, v34
	v_mul_f32_e32 v19, v31, v34
	v_mul_f32_e32 v20, v32, v34
	v_mul_f32_e32 v21, v33, v34
	global_store_dwordx2 v[36:37], v[2:3], off offset:96
	v_mul_f32_e32 v2, v14, v34
	v_mul_f32_e32 v3, v15, v34
	v_mul_f32_e32 v4, v16, v34
	v_mul_f32_e32 v5, v17, v34
	s_add_i32 s45, s45, s14
	v_cvt_pk_bf16_f32 v18, v18, v19
	v_cvt_pk_bf16_f32 v19, v20, v21
	v_cvt_pk_bf16_f32 v2, v2, v3
	v_cvt_pk_bf16_f32 v3, v4, v5
	s_cmpk_gt_i32 s45, 0x3ff
	global_store_dwordx2 v[36:37], v[18:19], off offset:48
	global_store_dwordx2 v[36:37], v[2:3], off offset:112
	s_cbranch_scc1 .LBB0_528

; template <int HD, int MODE> ...
;     ...
;             if constexpr (HD == 64) {
;                 bf16x8 kf0[HD / 16], kf1[HD / 16];
; #pragma unroll
;                 for (int d0 = 0; d0 < HD / 16; ++d0) { kf0[d0] = *(const LAS bf16x8*)(kb + d0 * 32); kf1[d0] = *(const LAS bf16x8*)(kb + 32 * KROW + d0 * 32); }
;                 __builtin_amdgcn_sched_barrier(0);
;                 __builtin_amdgcn_s_setprio(1);
; #pragma unroll
;                 for (int d0 = 0; d0 < HD / 16; ++d0) { s0 = __builtin_amdgcn_mfma_f32_32x32x16_bf16(kf0[d0], qf[d0], s0, 0, 0, 0); s1 = __builtin_amdgcn_mfma_f32_32x32x16_bf16(kf1[d0], qf[d0], s1, 0, 0, 0); }
;                 __builtin_amdgcn_s_setprio(0);
;             } else {
;             __builtin_amdgcn_s_setprio(1);
; #pragma unroll
;             for (int d0 = 0; d0 < HD / 16; ++d0) {
;                 const bf16x8 k0 = *(const LAS bf16x8*)(kb + d0 * 32);
;                 const bf16x8 k1 = *(const LAS bf16x8*)(kb + 32 * KROW + d0 * 32);
;                 s0 = __builtin_amdgcn_mfma_f32_32x32x16_bf16(k0, qf[d0], s0, 0, 0, 0);
;                 s1 = __builtin_amdgcn_mfma_f32_32x32x16_bf16(k1, qf[d0], s1, 0, 0, 0);
;             }
;             __builtin_amdgcn_s_setprio(0); }
;             if (MODE == 1) {
;                 const LAS float* bl = biasl + (64 * t + 8 * hi - (qlo + r32) + 384);
; #pragma unroll
;                 for (int r = 0; r < 16; ++r) { s0[r] += bl[16 * (r >> 3) + (r & 7)]; s1[r] += bl[32 + 16 * (r >> 3) + (r & 7)]; }
;             }
;             float mx = fmaxf(s0[0], s1[0]);
; #pragma unroll
;             for (int r = 1; r < 16; ++r) mx = fmaxf(mx, fmaxf(s0[r], s1[r]));
;             { auto rr = __builtin_amdgcn_permlane32_swap(__float_as_uint(mx), __float_as_uint(mx), false, false); mx = fmaxf(__uint_as_float(rr[0]), __uint_as_float(rr[1])); }
;             const float m_new = fmaxf(m_run, mx);
;             const bool grew = __any(m_new > m_run);
;             const float alpha = __builtin_amdgcn_exp2f(m_run - m_new);
;             m_run = m_new;
;             float rs = 0.f;
; #pragma unroll
;             for (int r = 0; r < 16; ++r) { s0[r] = __builtin_amdgcn_exp2f(s0[r] - m_new); s1[r] = __builtin_amdgcn_exp2f(s1[r] - m_new); rs += s0[r] + s1[r]; }
;             l_run = l_run * alpha + rs;
;             if (grew) {
; #pragma unroll
;                 for (int d0 = 0; d0 < HD / 32; ++d0)
; #pragma unroll
.LBB0_520:
	s_add_i32 s29, s6, 63
	s_cmp_ge_i32 s29, s10
	s_cselect_b64 s[46:47], -1, 0
	s_cmp_le_i32 s6, s11
	s_cselect_b64 s[48:49], -1, 0
	s_and_b64 s[46:47], s[46:47], s[48:49]
	s_andn2_b64 vcc, exec, s[46:47]
	s_cbranch_vccnz .LBB0_524
	s_mul_i32 s29, s17, 0x4800
	s_add_i32 s29, s29, 0
	v_add3_u32 v38, s29, v95, v0
	ds_read_b128 v[34:37], v38
	ds_read_b128 v[104:107], v38 offset:32
	ds_read_b128 v[50:53], v38 offset:4608
	ds_read_b128 v[108:111], v38 offset:4640
	ds_read_b128 v[112:115], v38 offset:64
	ds_read_b128 v[116:119], v38 offset:96
	ds_read_b128 v[120:123], v38 offset:4672
	ds_read_b128 v[124:127], v38 offset:4704
	s_setprio 1
	s_waitcnt lgkmcnt(7)
	v_mfma_f32_32x32x16_bf16 v[34:49], v[34:37], v[66:69], 0
	s_waitcnt lgkmcnt(5)
	v_mfma_f32_32x32x16_bf16 v[50:65], v[50:53], v[66:69], 0
	v_mfma_f32_32x32x16_bf16 v[34:49], v[104:107], v[70:73], v[34:49]
	s_waitcnt lgkmcnt(4)
	v_mfma_f32_32x32x16_bf16 v[50:65], v[108:111], v[70:73], v[50:65]
	s_waitcnt lgkmcnt(3)
	v_mfma_f32_32x32x16_bf16 v[34:49], v[112:115], v[74:77], v[34:49]
	s_waitcnt lgkmcnt(1)
	v_mfma_f32_32x32x16_bf16 v[50:65], v[120:123], v[74:77], v[50:65]
	ds_read2_b32 v[130:131], v100 offset1:1
	ds_read2_b32 v[132:133], v100 offset0:32 offset1:33
	ds_read2_b32 v[134:135], v100 offset0:2 offset1:3
	ds_read2_b32 v[136:137], v100 offset0:34 offset1:35
	ds_read2_b32 v[138:139], v100 offset0:4 offset1:5
	ds_read2_b32 v[140:141], v100 offset0:36 offset1:37
	ds_read2_b32 v[142:143], v100 offset0:6 offset1:7
	ds_read2_b32 v[144:145], v100 offset0:38 offset1:39
	ds_read2_b32 v[146:147], v100 offset0:16 offset1:17
	ds_read2_b32 v[148:149], v100 offset0:48 offset1:49
	ds_read2_b32 v[150:151], v100 offset0:18 offset1:19
	ds_read2_b32 v[152:153], v100 offset0:50 offset1:51
	ds_read2_b32 v[154:155], v100 offset0:20 offset1:21
	ds_read2_b32 v[156:157], v100 offset0:52 offset1:53
	v_mfma_f32_32x32x16_bf16 v[34:49], v[116:119], v[78:81], v[34:49]
	s_waitcnt lgkmcnt(14)
	v_mfma_f32_32x32x16_bf16 v[50:65], v[124:127], v[78:81], v[50:65]
	ds_read2_b32 v[158:159], v100 offset0:22 offset1:23
	ds_read2_b32 v[160:161], v100 offset0:54 offset1:55
	s_setprio 0
	s_waitcnt lgkmcnt(0)
	s_nop 10
	v_add_f32_e32 v107, v34, v130
	v_add_f32_e32 v106, v35, v131
	v_add_f32_e32 v110, v50, v132
	v_add_f32_e32 v105, v51, v133
	v_add_f32_e32 v103, v36, v134
	v_add_f32_e32 v51, v37, v135
	v_add_f32_e32 v104, v52, v136
	v_add_f32_e32 v50, v53, v137
	v_add_f32_e32 v52, v38, v138
	v_add_f32_e32 v37, v39, v139
	v_add_f32_e32 v53, v54, v140
	v_add_f32_e32 v36, v55, v141
	v_add_f32_e32 v40, v40, v142
	v_add_f32_e32 v111, v41, v143
	v_add_f32_e32 v112, v56, v144
	v_add_f32_e32 v108, v57, v145
	v_add_f32_e32 v109, v42, v146
	v_add_f32_e32 v57, v43, v147
	v_add_f32_e32 v58, v58, v148
	v_add_f32_e32 v56, v59, v149
	v_add_f32_e32 v54, v44, v150
	v_add_f32_e32 v43, v45, v151
	v_add_f32_e32 v42, v61, v153
	v_add_f32_e32 v55, v60, v152
	v_add_f32_e32 v44, v46, v154
	v_add_f32_e32 v39, v47, v155
	v_add_f32_e32 v45, v62, v156
	v_add_f32_e32 v38, v63, v157
	v_add_f32_e32 v41, v48, v158
	v_max_f32_e32 v34, v106, v105
	v_add_f32_e32 v47, v49, v159
	v_max3_f32 v34, v107, v110, v34
	v_max_f32_e32 v35, v103, v104
	v_max_f32_e32 v49, v51, v50
	v_max3_f32 v34, v34, v35, v49
	v_max_f32_e32 v35, v52, v53
	v_max_f32_e32 v49, v37, v36
	v_max3_f32 v34, v34, v35, v49
	v_max_f32_e32 v35, v40, v112
	v_max_f32_e32 v49, v111, v108
	v_max3_f32 v34, v34, v35, v49
	v_max_f32_e32 v35, v109, v58
	v_max_f32_e32 v49, v57, v56
	v_max3_f32 v34, v34, v35, v49
	v_max_f32_e32 v35, v54, v55
	v_max_f32_e32 v49, v43, v42
	v_add_f32_e32 v48, v64, v160
	v_add_f32_e32 v46, v65, v161
	v_max3_f32 v34, v34, v35, v49
	v_max_f32_e32 v35, v44, v45
	v_max_f32_e32 v49, v39, v38
	v_max3_f32 v34, v34, v35, v49
	v_max_f32_e32 v35, v41, v48
	v_max_f32_e32 v49, v47, v46
	v_max3_f32 v34, v34, v35, v49
	v_mov_b32_e32 v35, v34
	s_nop 1
	v_permlane32_swap_b32_e32 v34, v35
	v_max3_f32 v35, v102, v34, v35
	v_sub_f32_e32 v34, v102, v35
	v_exp_f32_e32 v34, v34
	v_cmp_gt_f32_e32 vcc, v35, v102
	s_cbranch_vccz .LBB0_523
	v_mul_f32_e32 v16, v16, v34
	v_mul_f32_e32 v17, v17, v34
	v_mul_f32_e32 v14, v14, v34
	v_mul_f32_e32 v15, v15, v34
	v_mul_f32_e32 v12, v12, v34
	v_mul_f32_e32 v13, v13, v34
	v_mul_f32_e32 v10, v10, v34
	v_mul_f32_e32 v11, v11, v34
	v_mul_f32_e32 v8, v8, v34
	v_mul_f32_e32 v9, v9, v34
	v_mul_f32_e32 v6, v6, v34
	v_mul_f32_e32 v7, v7, v34
	v_mul_f32_e32 v4, v4, v34
	v_mul_f32_e32 v5, v5, v34
	v_mul_f32_e32 v2, v2, v34
	v_mul_f32_e32 v3, v3, v34
	v_mul_f32_e32 v32, v32, v34
	v_mul_f32_e32 v33, v33, v34
	v_mul_f32_e32 v30, v30, v34
	v_mul_f32_e32 v31, v31, v34
	v_mul_f32_e32 v28, v28, v34
	v_mul_f32_e32 v29, v29, v34
	v_mul_f32_e32 v26, v26, v34
	v_mul_f32_e32 v27, v27, v34
	v_mul_f32_e32 v24, v24, v34
	v_mul_f32_e32 v25, v25, v34
	v_mul_f32_e32 v22, v22, v34
	v_mul_f32_e32 v23, v23, v34
	v_mul_f32_e32 v20, v20, v34
	v_mul_f32_e32 v21, v21, v34
	v_mul_f32_e32 v18, v18, v34
	v_mul_f32_e32 v19, v19, v34

; template <int HD, int MODE> ...
;     ...
;             const float alpha = __builtin_amdgcn_exp2f(m_run - m_new);
;             m_run = m_new;
;             float rs = 0.f;
; #pragma unroll
;             for (int r = 0; r < 16; ++r) { s0[r] = __builtin_amdgcn_exp2f(s0[r] - m_new); s1[r] = __builtin_amdgcn_exp2f(s1[r] - m_new); rs += s0[r] + s1[r]; }
;             l_run = l_run * alpha + rs;
;             if (grew) {
; #pragma unroll
;                 for (int d0 = 0; d0 < HD / 32; ++d0)
; #pragma unroll
;                     for (int r = 0; r < 16; ++r) o[d0][r] *= alpha;
;             }
;             bf16x8 pf[4];
;             { u32x4 w;
;               w.x = pk2(s0[0], s0[1]); w.y = pk2(s0[2], s0[3]); w.z = pk2(s0[4], s0[5]); w.w = pk2(s0[6], s0[7]); pf[0] = __builtin_bit_cast(bf16x8, w);
;               w.x = pk2(s0[8], s0[9]); w.y = pk2(s0[10], s0[11]); w.z = pk2(s0[12], s0[13]); w.w = pk2(s0[14], s0[15]); pf[1] = __builtin_bit_cast(bf16x8, w);
;               w.x = pk2(s1[0], s1[1]); w.y = pk2(s1[2], s1[3]); w.z = pk2(s1[4], s1[5]); w.w = pk2(s1[6], s1[7]); pf[2] = __builtin_bit_cast(bf16x8, w);
;               w.x = pk2(s1[8], s1[9]); w.y = pk2(s1[10], s1[11]); w.z = pk2(s1[12], s1[13]); w.w = pk2(s1[14], s1[15]); pf[3] = __builtin_bit_cast(bf16x8, w); }
;             if constexpr (HD == 64) {
;                 bf16x8 vfr[HD / 32][4];
; #pragma unroll
;                 for (int d0 = 0; d0 < HD / 32; ++d0)
; #pragma unroll
;                     for (int kk = 0; kk < 4; ++kk) vfr[d0][kk] = *(const LAS bf16x8*)(vb + d0 * 32 * VROW + kk * 32);
;                 __builtin_amdgcn_sched_barrier(0);
;                 __builtin_amdgcn_s_setprio(1);
; #pragma unroll
;                 for (int d0 = 0; d0 < HD / 32; ++d0)
; #pragma unroll
;                     for (int kk = 0; kk < 4; ++kk) o[d0] = __builtin_amdgcn_mfma_f32_32x32x16_bf16(vfr[d0][kk], pf[kk], o[d0], 0, 0, 0);
;                 __builtin_amdgcn_s_setprio(0);
;             } else {
;             __builtin_amdgcn_s_setprio(1);
; #pragma unroll
;             for (int d0 = 0; d0 < HD / 32; ++d0)
; #pragma unroll
;                 for (int kk = 0; kk < 4; ++kk) {
;                     const bf16x8 vf = *(const LAS bf16x8*)(vb + d0 * 32 * VROW + kk * 32);
;                     o[d0] = __builtin_amdgcn_mfma_f32_32x32x16_bf16(vf, pf[kk], o[d0], 0, 0, 0);
;                 }
.LBB0_530:
	v_sub_f32_e32 v4, v94, v0
	v_exp_f32_e32 v13, v4
	v_sub_f32_e32 v4, v95, v0
	v_exp_f32_e32 v12, v4
	v_sub_f32_e32 v4, v110, v0
	v_exp_f32_e32 v14, v4
	v_sub_f32_e32 v4, v111, v0
	v_exp_f32_e32 v94, v4
	v_sub_f32_e32 v4, v92, v0
	v_exp_f32_e32 v95, v4
	v_sub_f32_e32 v4, v93, v0
	v_exp_f32_e32 v92, v4
	v_sub_f32_e32 v4, v108, v0
	v_exp_f32_e32 v93, v4
	v_sub_f32_e32 v4, v109, v0
	v_exp_f32_e32 v108, v4
	v_sub_f32_e32 v4, v90, v0
	v_exp_f32_e32 v109, v4
	v_sub_f32_e32 v4, v91, v0
	v_exp_f32_e32 v110, v4
	v_sub_f32_e32 v4, v106, v0
	v_exp_f32_e32 v111, v4
	v_sub_f32_e32 v4, v107, v0
	v_exp_f32_e32 v106, v4
	v_sub_f32_e32 v4, v88, v0
	v_exp_f32_e32 v107, v4
	v_sub_f32_e32 v4, v89, v0
	v_exp_f32_e32 v112, v4
	v_sub_f32_e32 v4, v104, v0
	v_exp_f32_e32 v113, v4
	v_sub_f32_e32 v4, v105, v0
	v_exp_f32_e32 v104, v4
	v_sub_f32_e32 v4, v86, v0
	v_exp_f32_e32 v105, v4
	v_sub_f32_e32 v4, v87, v0
	v_exp_f32_e32 v114, v4
	v_sub_f32_e32 v4, v102, v0
	v_exp_f32_e32 v115, v4
	v_sub_f32_e32 v4, v103, v0
	v_exp_f32_e32 v102, v4
	v_sub_f32_e32 v4, v84, v0
	v_exp_f32_e32 v103, v4
	v_sub_f32_e32 v4, v85, v0
	v_exp_f32_e32 v116, v4
	v_sub_f32_e32 v4, v100, v0
	v_exp_f32_e32 v117, v4
	v_sub_f32_e32 v4, v101, v0
	v_exp_f32_e32 v100, v4
	v_sub_f32_e32 v4, v82, v0
	v_exp_f32_e32 v101, v4
	v_sub_f32_e32 v4, v83, v0
	v_exp_f32_e32 v118, v4
	v_sub_f32_e32 v4, v98, v0
	v_exp_f32_e32 v119, v4
	v_sub_f32_e32 v4, v99, v0
	v_sub_f32_e32 v5, v96, v0
	v_exp_f32_e32 v98, v4
	v_sub_f32_e32 v4, v80, v0
	v_exp_f32_e32 v99, v5
	v_sub_f32_e32 v5, v97, v0
	v_sub_f32_e32 v0, v81, v0
	s_lshl_b64 s[0:1], s[0:1], 10
	v_exp_f32_e32 v96, v5
	v_exp_f32_e32 v97, v4
	v_exp_f32_e32 v0, v0
	s_add_u32 s0, s17, s0
	s_addc_u32 s1, s21, s1
	s_add_u32 s0, s0, s2
	s_addc_u32 s1, s1, s3
	v_add3_u32 v3, s5, v151, v150
	v_cvt_pk_bf16_f32 v4, v99, v96
	v_cvt_pk_bf16_f32 v5, v119, v98
	v_cvt_pk_bf16_f32 v6, v117, v100
	v_cvt_pk_bf16_f32 v7, v115, v102
	v_cvt_pk_bf16_f32 v8, v113, v104
	v_cvt_pk_bf16_f32 v9, v111, v106
	v_cvt_pk_bf16_f32 v10, v93, v108
	v_cvt_pk_bf16_f32 v11, v14, v94
	v_cvt_pk_bf16_f32 v80, v97, v0
	v_cvt_pk_bf16_f32 v81, v101, v118
	v_cvt_pk_bf16_f32 v82, v103, v116
	v_cvt_pk_bf16_f32 v83, v105, v114
	v_cvt_pk_bf16_f32 v84, v107, v112
	v_cvt_pk_bf16_f32 v85, v109, v110
	v_cvt_pk_bf16_f32 v86, v95, v92
	v_cvt_pk_bf16_f32 v87, v13, v12
	s_setprio 1
	ds_read_b128 v[88:91], v3 offset:17408
	s_waitcnt lgkmcnt(0)
	v_mfma_f32_32x32x16_bf16 v[64:79], v[88:91], v[4:7], v[64:79]
	ds_read_b128 v[88:91], v3 offset:17440
	s_waitcnt lgkmcnt(0)
	v_mfma_f32_32x32x16_bf16 v[64:79], v[88:91], v[8:11], v[64:79]
	ds_read_b128 v[88:91], v3 offset:17472
	s_waitcnt lgkmcnt(0)
	v_mfma_f32_32x32x16_bf16 v[64:79], v[88:91], v[80:83], v[64:79]
	ds_read_b128 v[88:91], v3 offset:17504
	s_waitcnt lgkmcnt(0)
	v_mfma_f32_32x32x16_bf16 v[64:79], v[88:91], v[84:87], v[64:79]
	ds_read_b128 v[88:91], v3 offset:22016
	s_waitcnt lgkmcnt(0)
	v_mfma_f32_32x32x16_bf16 v[48:63], v[88:91], v[4:7], v[48:63]
	ds_read_b128 v[88:91], v3 offset:22048
	s_waitcnt lgkmcnt(0)
	v_mfma_f32_32x32x16_bf16 v[48:63], v[88:91], v[8:11], v[48:63]
	ds_read_b128 v[88:91], v3 offset:22080
	s_waitcnt lgkmcnt(0)
	v_mfma_f32_32x32x16_bf16 v[48:63], v[88:91], v[80:83], v[48:63]
	ds_read_b128 v[88:91], v3 offset:22112
	s_waitcnt lgkmcnt(0)
	v_mfma_f32_32x32x16_bf16 v[48:63], v[88:91], v[84:87], v[48:63]
	ds_read_b128 v[88:91], v3 offset:26624
	s_waitcnt lgkmcnt(0)
	v_mfma_f32_32x32x16_bf16 v[32:47], v[88:91], v[4:7], v[32:47]
	ds_read_b128 v[88:91], v3 offset:26656
	s_waitcnt lgkmcnt(0)
	v_mfma_f32_32x32x16_bf16 v[32:47], v[88:91], v[8:11], v[32:47]
	ds_read_b128 v[88:91], v3 offset:26688
	s_waitcnt lgkmcnt(0)
	v_mfma_f32_32x32x16_bf16 v[32:47], v[88:91], v[80:83], v[32:47]
	ds_read_b128 v[88:91], v3 offset:26720
	s_waitcnt lgkmcnt(0)
	v_mfma_f32_32x32x16_bf16 v[32:47], v[88:91], v[84:87], v[32:47]
	ds_read_b128 v[88:91], v3 offset:31232
	s_waitcnt lgkmcnt(0)
	v_mfma_f32_32x32x16_bf16 v[16:31], v[88:91], v[4:7], v[16:31]
	ds_read_b128 v[4:7], v3 offset:31264
	s_waitcnt lgkmcnt(0)
	v_mfma_f32_32x32x16_bf16 v[16:31], v[4:7], v[8:11], v[16:31]
	ds_read_b128 v[4:7], v3 offset:31296
	s_waitcnt lgkmcnt(0)
	v_mfma_f32_32x32x16_bf16 v[16:31], v[4:7], v[80:83], v[16:31]
	ds_read_b128 v[4:7], v3 offset:31328
	s_waitcnt lgkmcnt(0)
; template <int HD, int MODE> ...
;     ...
;             const float alpha = __builtin_amdgcn_exp2f(m_run - m_new);
;             m_run = m_new;
;             float rs = 0.f;
; #pragma unroll
;             for (int r = 0; r < 16; ++r) { s0[r] = __builtin_amdgcn_exp2f(s0[r] - m_new); s1[r] = __builtin_amdgcn_exp2f(s1[r] - m_new); rs += s0[r] + s1[r]; }
;             l_run = l_run * alpha + rs;
;             if (grew) {
; #pragma unroll
;                 for (int d0 = 0; d0 < HD / 32; ++d0)
; #pragma unroll
;                     for (int r = 0; r < 16; ++r) o[d0][r] *= alpha;
;             }
;             bf16x8 pf[4];
;             { u32x4 w;
;               w.x = pk2(s0[0], s0[1]); w.y = pk2(s0[2], s0[3]); w.z = pk2(s0[4], s0[5]); w.w = pk2(s0[6], s0[7]); pf[0] = __builtin_bit_cast(bf16x8, w);
;               w.x = pk2(s0[8], s0[9]); w.y = pk2(s0[10], s0[11]); w.z = pk2(s0[12], s0[13]); w.w = pk2(s0[14], s0[15]); pf[1] = __builtin_bit_cast(bf16x8, w);
;               w.x = pk2(s1[0], s1[1]); w.y = pk2(s1[2], s1[3]); w.z = pk2(s1[4], s1[5]); w.w = pk2(s1[6], s1[7]); pf[2] = __builtin_bit_cast(bf16x8, w);
;               w.x = pk2(s1[8], s1[9]); w.y = pk2(s1[10], s1[11]); w.z = pk2(s1[12], s1[13]); w.w = pk2(s1[14], s1[15]); pf[3] = __builtin_bit_cast(bf16x8, w); }
;             if constexpr (HD == 64) {
;                 bf16x8 vfr[HD / 32][4];
; #pragma unroll
;                 for (int d0 = 0; d0 < HD / 32; ++d0)
; #pragma unroll
;                     for (int kk = 0; kk < 4; ++kk) vfr[d0][kk] = *(const LAS bf16x8*)(vb + d0 * 32 * VROW + kk * 32);
;                 __builtin_amdgcn_sched_barrier(0);
;                 __builtin_amdgcn_s_setprio(1);
; #pragma unroll
;                 for (int d0 = 0; d0 < HD / 32; ++d0)
; #pragma unroll
;                     for (int kk = 0; kk < 4; ++kk) o[d0] = __builtin_amdgcn_mfma_f32_32x32x16_bf16(vfr[d0][kk], pf[kk], o[d0], 0, 0, 0);
;                 __builtin_amdgcn_s_setprio(0);
;             } else {
;             __builtin_amdgcn_s_setprio(1);
; #pragma unroll
;             for (int d0 = 0; d0 < HD / 32; ++d0)
; #pragma unroll
;                 for (int kk = 0; kk < 4; ++kk) {
;                     const bf16x8 vf = *(const LAS bf16x8*)(vb + d0 * 32 * VROW + kk * 32);
;                     o[d0] = __builtin_amdgcn_mfma_f32_32x32x16_bf16(vf, pf[kk], o[d0], 0, 0, 0);
;                 }
	v_mfma_f32_32x32x16_bf16 v[16:31], v[4:7], v[84:87], v[16:31]
	s_setprio 0
	v_add_f32_e32 v97, v99, v97
	v_add_f32_e64 v4, v96, v0
	v_add_f32_e64 v5, v97, v1
	v_add_f32_e32 v99, v119, v101
	v_add_f32_e32 v5, v4, v5
	v_add_f32_e32 v4, v4, v4
	v_mov_b32_e32 v119, v5
	v_add_f32_e32 v4, v98, v118
	v_add_f32_e32 v5, v99, v119
	v_add_f32_e32 v101, v117, v103
	v_add_f32_e32 v5, v4, v5
	v_add_f32_e32 v4, v4, v4
	v_mov_b32_e32 v117, v5
	v_add_f32_e32 v4, v100, v116
	v_add_f32_e32 v5, v101, v117
	v_add_f32_e32 v103, v115, v105
	v_add_f32_e32 v5, v4, v5
	v_add_f32_e32 v4, v4, v4
	v_mov_b32_e32 v115, v5
	v_add_f32_e32 v4, v102, v114
	v_add_f32_e32 v5, v103, v115
	v_add_f32_e32 v105, v113, v107
	v_add_f32_e32 v5, v4, v5
	v_add_f32_e32 v4, v4, v4
	v_mov_b32_e32 v113, v5
	v_add_f32_e32 v4, v104, v112
	v_add_f32_e32 v5, v105, v113
	v_add_f32_e32 v107, v111, v109
	v_add_f32_e32 v5, v4, v5
	v_add_f32_e32 v4, v4, v4
	v_mov_b32_e32 v111, v5
	v_add_f32_e32 v4, v106, v110
	v_add_f32_e32 v5, v107, v111
	v_add_f32_e32 v109, v93, v95
	v_add_f32_e32 v5, v4, v5
	v_add_f32_e32 v4, v4, v4
	v_mov_b32_e32 v93, v5
	v_add_f32_e32 v4, v108, v92
	v_add_f32_e32 v5, v109, v93
	v_add_f32_e32 v95, v14, v13
	v_add_f32_e32 v5, v4, v5
	v_add_f32_e32 v4, v4, v4
	v_mov_b32_e32 v13, v5
	v_add_f32_e32 v4, v94, v12
	v_add_f32_e32 v5, v95, v13
	s_add_i32 s43, s43, s14
	v_add_f32_e32 v0, v4, v5
	v_fmac_f32_e32 v0, v15, v2
	v_mov_b32_e32 v2, v0
	s_nop 1
	v_permlane32_swap_b32_e32 v0, v2
	v_add_f32_e32 v0, v0, v2
	v_div_scale_f32 v2, s[2:3], v0, v0, 1.0
	v_rcp_f32_e32 v3, v2
	s_cmpk_gt_i32 s43, 0x1ff
	v_fma_f32 v4, -v2, v3, 1.0
	v_fmac_f32_e32 v3, v4, v3
	v_div_scale_f32 v4, vcc, 1.0, v0, 1.0
	v_mul_f32_e32 v5, v4, v3
	v_fma_f32 v6, -v2, v5, v4
	v_fmac_f32_e32 v5, v6, v3
	v_fma_f32 v2, -v2, v5, v4
	v_div_fmas_f32 v2, v2, v3, v5
	v_div_fixup_f32 v2, v2, v0, 1.0
	v_lshlrev_b64 v[4:5], 10, v[148:149]
	v_lshl_add_u64 v[4:5], s[0:1], 0, v[4:5]
	v_lshlrev_b32_e32 v0, 3, v164
	v_mul_f32_e32 v6, v64, v2
	v_mul_f32_e32 v7, v65, v2
	v_mul_f32_e32 v8, v66, v2
	v_mul_f32_e32 v9, v67, v2
	v_lshl_add_u64 v[4:5], v[4:5], 0, v[0:1]
	v_cvt_pk_bf16_f32 v6, v6, v7
	v_cvt_pk_bf16_f32 v7, v8, v9
	global_store_dwordx2 v[4:5], v[6:7], off
	v_mul_f32_e32 v6, v68, v2
	v_mul_f32_e32 v7, v69, v2
	v_mul_f32_e32 v8, v70, v2
	v_mul_f32_e32 v9, v71, v2
	v_cvt_pk_bf16_f32 v6, v6, v7
	v_cvt_pk_bf16_f32 v7, v8, v9
	global_store_dwordx2 v[4:5], v[6:7], off offset:16
	v_mul_f32_e32 v6, v72, v2
	v_mul_f32_e32 v7, v73, v2
	v_mul_f32_e32 v8, v74, v2
	v_mul_f32_e32 v9, v75, v2
	v_cvt_pk_bf16_f32 v6, v6, v7
	v_cvt_pk_bf16_f32 v7, v8, v9
	global_store_dwordx2 v[4:5], v[6:7], off offset:32
	v_mul_f32_e32 v6, v76, v2
	v_mul_f32_e32 v7, v77, v2
	v_mul_f32_e32 v8, v78, v2
	v_mul_f32_e32 v9, v79, v2
	v_cvt_pk_bf16_f32 v6, v6, v7
	v_cvt_pk_bf16_f32 v7, v8, v9
	global_store_dwordx2 v[4:5], v[6:7], off offset:48
	v_mul_f32_e32 v6, v48, v2
	v_mul_f32_e32 v7, v49, v2
	v_mul_f32_e32 v8, v50, v2
	v_mul_f32_e32 v9, v51, v2
	v_cvt_pk_bf16_f32 v6, v6, v7
	v_cvt_pk_bf16_f32 v7, v8, v9
	global_store_dwordx2 v[4:5], v[6:7], off offset:64
	v_mul_f32_e32 v6, v52, v2
	v_mul_f32_e32 v7, v53, v2
	v_mul_f32_e32 v8, v54, v2
	v_mul_f32_e32 v9, v55, v2
	v_cvt_pk_bf16_f32 v6, v6, v7
	v_cvt_pk_bf16_f32 v7, v8, v9
	global_store_dwordx2 v[4:5], v[6:7], off offset:80
	v_mul_f32_e32 v6, v56, v2
	v_mul_f32_e32 v7, v57, v2
	v_mul_f32_e32 v8, v58, v2
	v_mul_f32_e32 v9, v59, v2
	v_cvt_pk_bf16_f32 v6, v6, v7
	v_cvt_pk_bf16_f32 v7, v8, v9
	global_store_dwordx2 v[4:5], v[6:7], off offset:96
	v_mul_f32_e32 v6, v60, v2
	v_mul_f32_e32 v7, v61, v2
	v_mul_f32_e32 v8, v62, v2
	v_mul_f32_e32 v9, v63, v2
	v_cvt_pk_bf16_f32 v6, v6, v7
	v_cvt_pk_bf16_f32 v7, v8, v9
	global_store_dwordx2 v[4:5], v[6:7], off offset:112
	v_mul_f32_e32 v6, v32, v2
	v_mul_f32_e32 v7, v33, v2
	v_mul_f32_e32 v8, v34, v2
	v_mul_f32_e32 v9, v35, v2
	v_cvt_pk_bf16_f32 v6, v6, v7
	v_cvt_pk_bf16_f32 v7, v8, v9
	global_store_dwordx2 v[4:5], v[6:7], off offset:128
	v_mul_f32_e32 v6, v36, v2
	v_mul_f32_e32 v7, v37, v2
	v_mul_f32_e32 v8, v38, v2
	v_mul_f32_e32 v9, v39, v2
	v_cvt_pk_bf16_f32 v6, v6, v7
	v_cvt_pk_bf16_f32 v7, v8, v9
	global_store_dwordx2 v[4:5], v[6:7], off offset:144
	v_mul_f32_e32 v6, v40, v2
	v_mul_f32_e32 v7, v41, v2
	v_mul_f32_e32 v8, v42, v2
	v_mul_f32_e32 v9, v43, v2
	v_cvt_pk_bf16_f32 v6, v6, v7
	v_cvt_pk_bf16_f32 v7, v8, v9
	global_store_dwordx2 v[4:5], v[6:7], off offset:160
	v_mul_f32_e32 v6, v44, v2
	v_mul_f32_e32 v7, v45, v2
	v_mul_f32_e32 v8, v46, v2
	v_mul_f32_e32 v9, v47, v2
	v_cvt_pk_bf16_f32 v6, v6, v7
	v_cvt_pk_bf16_f32 v7, v8, v9
	global_store_dwordx2 v[4:5], v[6:7], off offset:176
	v_mul_f32_e32 v6, v16, v2
	v_mul_f32_e32 v7, v17, v2
	v_mul_f32_e32 v8, v18, v2
	v_mul_f32_e32 v9, v19, v2
	v_cvt_pk_bf16_f32 v6, v6, v7
	v_cvt_pk_bf16_f32 v7, v8, v9
	global_store_dwordx2 v[4:5], v[6:7], off offset:192
	v_mul_f32_e32 v6, v20, v2
	v_mul_f32_e32 v7, v21, v2
	v_mul_f32_e32 v8, v22, v2
	v_mul_f32_e32 v9, v23, v2
	v_cvt_pk_bf16_f32 v6, v6, v7
	v_cvt_pk_bf16_f32 v7, v8, v9
	global_store_dwordx2 v[4:5], v[6:7], off offset:208
	v_mul_f32_e32 v6, v24, v2
	v_mul_f32_e32 v7, v25, v2
	v_mul_f32_e32 v8, v26, v2
	v_mul_f32_e32 v9, v27, v2
	v_cvt_pk_bf16_f32 v6, v6, v7
	v_cvt_pk_bf16_f32 v7, v8, v9
	global_store_dwordx2 v[4:5], v[6:7], off offset:224
	v_mul_f32_e32 v6, v28, v2
	v_mul_f32_e32 v7, v29, v2
	v_mul_f32_e32 v3, v31, v2
	v_mul_f32_e32 v2, v30, v2
	v_cvt_pk_bf16_f32 v6, v6, v7
	v_cvt_pk_bf16_f32 v7, v2, v3
	global_store_dwordx2 v[4:5], v[6:7], off offset:240
	s_cbranch_scc1 .LBB0_538

; template <int HD, int MODE> ...
;     ...
;     for (int t = t0; t < t1; ++t) {
;         __syncthreads();
;         const bool more = (t + 1 < t1);
;         if (more) ATT_LOAD(t + 1);
;         bool active = true;
;         if (MODE == 1) active = !(64 * t + 63 < qlo - 128 || 64 * t > qlo + 31 + 128);
;         if (active) {
;             const LAS unsigned char* kb = lds + cur * BUF + krd;
;             const LAS unsigned char* vb = lds + cur * BUF + vrd;
;             f32x16 s0, s1;
; #pragma unroll
;             for (int r = 0; r < 16; ++r) { s0[r] = 0.f; s1[r] = 0.f; }
;             if constexpr (HD == 64) {
;                 bf16x8 kf0[HD / 16], kf1[HD / 16];
; #pragma unroll
;                 for (int d0 = 0; d0 < HD / 16; ++d0) { kf0[d0] = *(const LAS bf16x8*)(kb + d0 * 32); kf1[d0] = *(const LAS bf16x8*)(kb + 32 * KROW + d0 * 32); }
;                 __builtin_amdgcn_sched_barrier(0);
;                 __builtin_amdgcn_s_setprio(1);
; #pragma unroll
;                 for (int d0 = 0; d0 < HD / 16; ++d0) { s0 = __builtin_amdgcn_mfma_f32_32x32x16_bf16(kf0[d0], qf[d0], s0, 0, 0, 0); s1 = __builtin_amdgcn_mfma_f32_32x32x16_bf16(kf1[d0], qf[d0], s1, 0, 0, 0); }
;                 __builtin_amdgcn_s_setprio(0);
;             } else {
;             __builtin_amdgcn_s_setprio(1);
; #pragma unroll
;             for (int d0 = 0; d0 < HD / 16; ++d0) {
;                 const bf16x8 k0 = *(const LAS bf16x8*)(kb + d0 * 32);
;                 const bf16x8 k1 = *(const LAS bf16x8*)(kb + 32 * KROW + d0 * 32);
;                 s0 = __builtin_amdgcn_mfma_f32_32x32x16_bf16(k0, qf[d0], s0, 0, 0, 0);
;                 s1 = __builtin_amdgcn_mfma_f32_32x32x16_bf16(k1, qf[d0], s1, 0, 0, 0);
;             }
;             __builtin_amdgcn_s_setprio(0); }
;             if (MODE == 1) {
;                 const LAS float* bl = biasl + (64 * t + 8 * hi - (qlo + r32) + 384);
; #pragma unroll
;                 for (int r = 0; r < 16; ++r) { s0[r] += bl[16 * (r >> 3) + (r & 7)]; s1[r] += bl[32 + 16 * (r >> 3) + (r & 7)]; }
;             }
;             float mx = fmaxf(s0[0], s1[0]);
; #pragma unroll
;             for (int r = 1; r < 16; ++r) mx = fmaxf(mx, fmaxf(s0[r], s1[r]));
;             { auto rr = __builtin_amdgcn_permlane32_swap(__float_as_uint(mx), __float_as_uint(mx), false, false); mx = fmaxf(__uint_as_float(rr[0]), __uint_as_float(rr[1])); }
.LBB0_532:
	v_lshl_add_u64 v[2:3], s[84:85], 0, v[162:163]
	v_lshl_add_u64 v[4:5], s[84:85], 0, v[158:159]
	v_lshl_add_u64 v[10:11], s[84:85], 0, v[160:161]
	v_lshl_add_u64 v[12:13], s[84:85], 0, v[156:157]
	s_waitcnt lgkmcnt(0)
	s_barrier
	global_load_dwordx4 v[6:9], v[2:3], off
	s_nop 0
	global_load_dwordx4 v[2:5], v[4:5], off
	s_nop 0
	global_load_dwordx4 v[144:147], v[10:11], off
	s_nop 0
	global_load_dwordx4 v[10:13], v[12:13], off
	s_mul_i32 s5, s4, 0x8c00
	s_add_i32 s5, s5, 0
	v_add3_u32 v14, s5, v167, v150
	v_mov_b32_e32 v0, v153
	s_setprio 1
	ds_read_b128 v[80:83], v14
	ds_read_b128 v[168:171], v14 offset:32
	ds_read_b128 v[96:99], v14 offset:8704
	s_waitcnt lgkmcnt(2)
	v_mfma_f32_32x32x16_bf16 v[80:95], v[80:83], v[140:143], 0
	s_waitcnt lgkmcnt(1)
	v_mfma_f32_32x32x16_bf16 v[80:95], v[168:171], v[136:139], v[80:95]
	ds_read_b128 v[168:171], v14 offset:8736
	s_waitcnt lgkmcnt(1)
	v_mfma_f32_32x32x16_bf16 v[96:111], v[96:99], v[140:143], 0
	s_waitcnt lgkmcnt(0)
	v_mfma_f32_32x32x16_bf16 v[96:111], v[168:171], v[136:139], v[96:111]
	ds_read_b128 v[168:171], v14 offset:64
	s_waitcnt lgkmcnt(0)
	v_mfma_f32_32x32x16_bf16 v[80:95], v[168:171], v[132:135], v[80:95]
	ds_read_b128 v[168:171], v14 offset:8768
	s_waitcnt lgkmcnt(0)
	v_mfma_f32_32x32x16_bf16 v[96:111], v[168:171], v[132:135], v[96:111]
	ds_read_b128 v[168:171], v14 offset:96
	s_waitcnt lgkmcnt(0)
	v_mfma_f32_32x32x16_bf16 v[80:95], v[168:171], v[128:131], v[80:95]
	ds_read_b128 v[168:171], v14 offset:8800
	s_waitcnt lgkmcnt(0)
	v_mfma_f32_32x32x16_bf16 v[96:111], v[168:171], v[128:131], v[96:111]
	ds_read_b128 v[168:171], v14 offset:128
	s_waitcnt lgkmcnt(0)
	v_mfma_f32_32x32x16_bf16 v[80:95], v[168:171], v[124:127], v[80:95]
	ds_read_b128 v[168:171], v14 offset:8832
	s_waitcnt lgkmcnt(0)
	v_mfma_f32_32x32x16_bf16 v[96:111], v[168:171], v[124:127], v[96:111]
	ds_read_b128 v[168:171], v14 offset:160
	s_waitcnt lgkmcnt(0)
	v_mfma_f32_32x32x16_bf16 v[80:95], v[168:171], v[120:123], v[80:95]
	ds_read_b128 v[168:171], v14 offset:8864
	s_waitcnt lgkmcnt(0)
	v_mfma_f32_32x32x16_bf16 v[96:111], v[168:171], v[120:123], v[96:111]
	ds_read_b128 v[168:171], v14 offset:192
	s_waitcnt lgkmcnt(0)
	v_mfma_f32_32x32x16_bf16 v[80:95], v[168:171], v[116:119], v[80:95]
	ds_read_b128 v[168:171], v14 offset:8896
	s_waitcnt lgkmcnt(0)
	v_mfma_f32_32x32x16_bf16 v[96:111], v[168:171], v[116:119], v[96:111]
	ds_read_b128 v[168:171], v14 offset:224
	s_waitcnt lgkmcnt(0)
	v_mfma_f32_32x32x16_bf16 v[80:95], v[168:171], v[112:115], v[80:95]
	ds_read_b128 v[168:171], v14 offset:8928
	s_waitcnt lgkmcnt(0)
	v_mfma_f32_32x32x16_bf16 v[96:111], v[168:171], v[112:115], v[96:111]
	s_setprio 0
	s_nop 10
	v_max_f32_e32 v14, v97, v97
	v_max_f32_e32 v15, v81, v81
	v_max_f32_e32 v14, v15, v14
	v_max_f32_e32 v15, v98, v98
	v_max_f32_e32 v153, v82, v82
	v_max_f32_e32 v15, v153, v15
	v_max_f32_e32 v153, v99, v99
	v_max_f32_e32 v168, v83, v83
	v_max3_f32 v14, v80, v96, v14
	v_max_f32_e32 v153, v168, v153
	v_max3_f32 v14, v14, v15, v153
	v_max_f32_e32 v15, v100, v100
	v_max_f32_e32 v153, v84, v84
	v_max_f32_e32 v15, v153, v15
	v_max_f32_e32 v153, v101, v101
	v_max_f32_e32 v168, v85, v85
	v_max_f32_e32 v153, v168, v153
	v_max3_f32 v14, v14, v15, v153
	v_max_f32_e32 v15, v102, v102
	v_max_f32_e32 v153, v86, v86
	v_max_f32_e32 v15, v153, v15
	v_max_f32_e32 v153, v103, v103
	v_max_f32_e32 v168, v87, v87
	v_max_f32_e32 v153, v168, v153
	v_max3_f32 v14, v14, v15, v153
	v_max_f32_e32 v15, v104, v104
	v_max_f32_e32 v153, v88, v88
	v_max_f32_e32 v15, v153, v15
	v_max_f32_e32 v153, v105, v105
	v_max_f32_e32 v168, v89, v89
	v_max_f32_e32 v153, v168, v153
	v_max3_f32 v14, v14, v15, v153
	v_max_f32_e32 v15, v106, v106
	v_max_f32_e32 v153, v90, v90
	v_max_f32_e32 v15, v153, v15
	v_max_f32_e32 v153, v107, v107
	v_max_f32_e32 v168, v91, v91
	v_max_f32_e32 v153, v168, v153
	v_max3_f32 v14, v14, v15, v153
	v_max_f32_e32 v15, v108, v108
	v_max_f32_e32 v153, v92, v92
	v_max_f32_e32 v15, v153, v15
	v_max_f32_e32 v153, v109, v109
	v_max_f32_e32 v168, v93, v93
	v_max_f32_e32 v153, v168, v153
	v_max3_f32 v14, v14, v15, v153
	v_max_f32_e32 v15, v110, v110
	v_max_f32_e32 v153, v94, v94
	v_max_f32_e32 v15, v153, v15
	v_max_f32_e32 v153, v111, v111
	v_max_f32_e32 v168, v95, v95
	v_max_f32_e32 v153, v168, v153
	v_max3_f32 v14, v14, v15, v153
	v_mov_b32_e32 v15, v14
	s_nop 1
	v_permlane32_swap_b32_e32 v14, v15
	v_max3_f32 v153, v0, v14, v15
	v_sub_f32_e32 v14, v0, v153
	v_exp_f32_e32 v14, v14
	v_cmp_gt_f32_e32 vcc, v153, v0
	s_cbranch_vccz .LBB0_534
	v_mul_f32_e32 v78, v78, v14
	v_mul_f32_e32 v79, v79, v14
	v_mul_f32_e32 v76, v76, v14
	v_mul_f32_e32 v77, v77, v14
	v_mul_f32_e32 v74, v74, v14
	v_mul_f32_e32 v75, v75, v14
	v_mul_f32_e32 v72, v72, v14
	v_mul_f32_e32 v73, v73, v14
	v_mul_f32_e32 v70, v70, v14
	v_mul_f32_e32 v71, v71, v14
	v_mul_f32_e32 v68, v68, v14
	v_mul_f32_e32 v69, v69, v14
	v_mul_f32_e32 v66, v66, v14
	v_mul_f32_e32 v67, v67, v14
	v_mul_f32_e32 v64, v64, v14
	v_mul_f32_e32 v65, v65, v14
	v_mul_f32_e32 v62, v62, v14
	v_mul_f32_e32 v63, v63, v14
	v_mul_f32_e32 v60, v60, v14
	v_mul_f32_e32 v61, v61, v14
	v_mul_f32_e32 v58, v58, v14
	v_mul_f32_e32 v59, v59, v14
	v_mul_f32_e32 v56, v56, v14
	v_mul_f32_e32 v57, v57, v14
	v_mul_f32_e32 v54, v54, v14
	v_mul_f32_e32 v55, v55, v14
	v_mul_f32_e32 v52, v52, v14
	v_mul_f32_e32 v53, v53, v14
	v_mul_f32_e32 v50, v50, v14
	v_mul_f32_e32 v51, v51, v14
	v_mul_f32_e32 v48, v48, v14
	v_mul_f32_e32 v49, v49, v14
	v_mul_f32_e32 v46, v46, v14
	v_mul_f32_e32 v47, v47, v14
	v_mul_f32_e32 v44, v44, v14
	v_mul_f32_e32 v45, v45, v14
	v_mul_f32_e32 v42, v42, v14
	v_mul_f32_e32 v43, v43, v14
	v_mul_f32_e32 v40, v40, v14
	v_mul_f32_e32 v41, v41, v14
	v_mul_f32_e32 v38, v38, v14
	v_mul_f32_e32 v39, v39, v14
	v_mul_f32_e32 v36, v36, v14
	v_mul_f32_e32 v37, v37, v14
	v_mul_f32_e32 v34, v34, v14
	v_mul_f32_e32 v35, v35, v14
	v_mul_f32_e32 v32, v32, v14
	v_mul_f32_e32 v33, v33, v14
	v_mul_f32_e32 v30, v30, v14
	v_mul_f32_e32 v31, v31, v14
	v_mul_f32_e32 v28, v28, v14
	v_mul_f32_e32 v29, v29, v14
	v_mul_f32_e32 v26, v26, v14
	v_mul_f32_e32 v27, v27, v14
	v_mul_f32_e32 v24, v24, v14
	v_mul_f32_e32 v25, v25, v14
	v_mul_f32_e32 v22, v22, v14
	v_mul_f32_e32 v23, v23, v14
	v_mul_f32_e32 v20, v20, v14
	v_mul_f32_e32 v21, v21, v14
	v_mul_f32_e32 v18, v18, v14
	v_mul_f32_e32 v19, v19, v14
	v_mul_f32_e32 v16, v16, v14
	v_mul_f32_e32 v17, v17, v14
; template <int HD, int MODE> ...
;     ...
;             const float alpha = __builtin_amdgcn_exp2f(m_run - m_new);
;             m_run = m_new;
;             float rs = 0.f;
; #pragma unroll
;             for (int r = 0; r < 16; ++r) { s0[r] = __builtin_amdgcn_exp2f(s0[r] - m_new); s1[r] = __builtin_amdgcn_exp2f(s1[r] - m_new); rs += s0[r] + s1[r]; }
;             l_run = l_run * alpha + rs;
;             if (grew) {
; #pragma unroll
;                 for (int d0 = 0; d0 < HD / 32; ++d0)
; #pragma unroll
;                     for (int r = 0; r < 16; ++r) o[d0][r] *= alpha;
;             }
;             bf16x8 pf[4];
;             { u32x4 w;
;               w.x = pk2(s0[0], s0[1]); w.y = pk2(s0[2], s0[3]); w.z = pk2(s0[4], s0[5]); w.w = pk2(s0[6], s0[7]); pf[0] = __builtin_bit_cast(bf16x8, w);
;               w.x = pk2(s0[8], s0[9]); w.y = pk2(s0[10], s0[11]); w.z = pk2(s0[12], s0[13]); w.w = pk2(s0[14], s0[15]); pf[1] = __builtin_bit_cast(bf16x8, w);
;               w.x = pk2(s1[0], s1[1]); w.y = pk2(s1[2], s1[3]); w.z = pk2(s1[4], s1[5]); w.w = pk2(s1[6], s1[7]); pf[2] = __builtin_bit_cast(bf16x8, w);
;               w.x = pk2(s1[8], s1[9]); w.y = pk2(s1[10], s1[11]); w.z = pk2(s1[12], s1[13]); w.w = pk2(s1[14], s1[15]); pf[3] = __builtin_bit_cast(bf16x8, w); }
;             if constexpr (HD == 64) {
;                 bf16x8 vfr[HD / 32][4];
; #pragma unroll
;                 for (int d0 = 0; d0 < HD / 32; ++d0)
; #pragma unroll
;                     for (int kk = 0; kk < 4; ++kk) vfr[d0][kk] = *(const LAS bf16x8*)(vb + d0 * 32 * VROW + kk * 32);
;                 __builtin_amdgcn_sched_barrier(0);
;                 __builtin_amdgcn_s_setprio(1);
; #pragma unroll
;                 for (int d0 = 0; d0 < HD / 32; ++d0)
; #pragma unroll
;                     for (int kk = 0; kk < 4; ++kk) o[d0] = __builtin_amdgcn_mfma_f32_32x32x16_bf16(vfr[d0][kk], pf[kk], o[d0], 0, 0, 0);
;                 __builtin_amdgcn_s_setprio(0);
;             } else {
;             __builtin_amdgcn_s_setprio(1);
; #pragma unroll
;             for (int d0 = 0; d0 < HD / 32; ++d0)
; #pragma unroll
;                 for (int kk = 0; kk < 4; ++kk) {
;                     const bf16x8 vf = *(const LAS bf16x8*)(vb + d0 * 32 * VROW + kk * 32);
;                     o[d0] = __builtin_amdgcn_mfma_f32_32x32x16_bf16(vf, pf[kk], o[d0], 0, 0, 0);
;                 }
.LBB0_534:
	v_sub_f32_e32 v0, v80, v153
	v_exp_f32_e32 v168, v0
	v_sub_f32_e32 v0, v96, v153
	v_exp_f32_e32 v169, v0
	v_sub_f32_e32 v0, v81, v153
	v_exp_f32_e32 v80, v0
	v_sub_f32_e32 v0, v97, v153
	v_exp_f32_e32 v0, v0
	v_add_f32_e32 v81, v168, v169
	v_sub_f32_e32 v15, v82, v153
	v_add_f32_e32 v96, v80, v0
	v_add_f32_e32 v97, v81, v1
	v_exp_f32_e32 v81, v15
	v_sub_f32_e32 v15, v98, v153
	v_exp_f32_e32 v170, v15
	v_sub_f32_e32 v15, v83, v153
	v_add_f32_e32 v97, v96, v97
	v_add_f32_e32 v96, v96, v96
	v_exp_f32_e32 v82, v15
	v_sub_f32_e32 v15, v99, v153
	v_exp_f32_e32 v96, v15
	v_add_f32_e32 v83, v81, v170
	v_sub_f32_e32 v15, v84, v153
	v_cvt_pk_bf16_f32 v80, v168, v80
	v_add_f32_e32 v98, v82, v96
	v_add_f32_e32 v99, v83, v97
	v_exp_f32_e32 v83, v15
	v_sub_f32_e32 v15, v100, v153
	v_exp_f32_e32 v97, v15
	v_sub_f32_e32 v15, v85, v153
	v_add_f32_e32 v99, v98, v99
	v_add_f32_e32 v98, v98, v98
	v_exp_f32_e32 v84, v15
	v_sub_f32_e32 v15, v101, v153
	v_exp_f32_e32 v98, v15
	v_add_f32_e32 v85, v83, v97
	v_sub_f32_e32 v15, v86, v153
	v_cvt_pk_bf16_f32 v81, v81, v82
	v_add_f32_e32 v100, v84, v98
	v_add_f32_e32 v101, v85, v99
	v_exp_f32_e32 v85, v15
	v_sub_f32_e32 v15, v102, v153
	v_exp_f32_e32 v99, v15
	v_sub_f32_e32 v15, v87, v153
	v_add_f32_e32 v101, v100, v101
	v_add_f32_e32 v100, v100, v100
	v_exp_f32_e32 v86, v15
	v_sub_f32_e32 v15, v103, v153
	v_exp_f32_e32 v100, v15
	v_add_f32_e32 v87, v85, v99
	v_sub_f32_e32 v15, v88, v153
	v_cvt_pk_bf16_f32 v82, v83, v84
	v_add_f32_e32 v102, v86, v100
	v_add_f32_e32 v103, v87, v101
	v_exp_f32_e32 v87, v15
	v_sub_f32_e32 v15, v104, v153
	v_exp_f32_e32 v101, v15
	v_sub_f32_e32 v15, v89, v153
	v_add_f32_e32 v103, v102, v103
	v_add_f32_e32 v102, v102, v102
	v_exp_f32_e32 v88, v15
	v_sub_f32_e32 v15, v105, v153
	v_exp_f32_e32 v102, v15
	v_add_f32_e32 v89, v87, v101
	v_sub_f32_e32 v15, v90, v153
	v_cvt_pk_bf16_f32 v83, v85, v86
	v_add_f32_e32 v104, v88, v102
	v_add_f32_e32 v105, v89, v103
	v_exp_f32_e32 v89, v15
	v_sub_f32_e32 v15, v106, v153
	v_exp_f32_e32 v103, v15
	v_sub_f32_e32 v15, v91, v153
	v_add_f32_e32 v105, v104, v105
	v_add_f32_e32 v104, v104, v104
	v_exp_f32_e32 v90, v15
	v_sub_f32_e32 v15, v107, v153
	v_exp_f32_e32 v104, v15
	v_add_f32_e32 v91, v89, v103
	v_sub_f32_e32 v15, v92, v153
	v_cvt_pk_bf16_f32 v84, v87, v88
	v_add_f32_e32 v106, v90, v104
	v_add_f32_e32 v107, v91, v105
	v_exp_f32_e32 v91, v15
	v_sub_f32_e32 v15, v108, v153
	v_exp_f32_e32 v105, v15
	v_sub_f32_e32 v15, v93, v153
	v_add_f32_e32 v107, v106, v107
	v_add_f32_e32 v106, v106, v106
	v_exp_f32_e32 v92, v15
	v_sub_f32_e32 v15, v109, v153
	v_exp_f32_e32 v106, v15
	v_add_f32_e32 v93, v91, v105
	v_sub_f32_e32 v15, v94, v153
	v_cvt_pk_bf16_f32 v85, v89, v90
	v_add_f32_e32 v108, v92, v106
	v_add_f32_e32 v109, v93, v107
	v_exp_f32_e32 v93, v15
	v_sub_f32_e32 v15, v110, v153
	v_exp_f32_e32 v107, v15
	v_sub_f32_e32 v15, v95, v153
	v_add_f32_e32 v109, v108, v109
	v_add_f32_e32 v108, v108, v108
	v_exp_f32_e32 v94, v15
	v_sub_f32_e32 v15, v111, v153
	v_exp_f32_e32 v108, v15
	v_add_f32_e32 v95, v93, v107
	v_cvt_pk_bf16_f32 v86, v91, v92
	v_cvt_pk_bf16_f32 v87, v93, v94
	v_add_f32_e32 v110, v94, v108
	v_add_f32_e32 v111, v95, v109
	v_cvt_pk_bf16_f32 v88, v169, v0
	v_add_f32_e32 v15, v110, v111
	v_fmac_f32_e32 v15, v155, v14
	v_cvt_pk_bf16_f32 v89, v170, v96
	v_cvt_pk_bf16_f32 v90, v97, v98
	v_cvt_pk_bf16_f32 v91, v99, v100
	v_cvt_pk_bf16_f32 v92, v101, v102
	v_cvt_pk_bf16_f32 v93, v103, v104
	v_cvt_pk_bf16_f32 v94, v105, v106
	v_cvt_pk_bf16_f32 v95, v107, v108
	s_setprio 1
	v_add3_u32 v0, s5, v151, v150
	ds_read_b128 v[96:99], v0 offset:17408
	s_waitcnt lgkmcnt(0)
	v_mfma_f32_32x32x16_bf16 v[64:79], v[96:99], v[80:83], v[64:79]
	ds_read_b128 v[96:99], v0 offset:17440
	s_waitcnt lgkmcnt(0)
	v_mfma_f32_32x32x16_bf16 v[64:79], v[96:99], v[84:87], v[64:79]
	ds_read_b128 v[96:99], v0 offset:17472
	s_waitcnt lgkmcnt(0)
	v_mfma_f32_32x32x16_bf16 v[64:79], v[96:99], v[88:91], v[64:79]
	ds_read_b128 v[96:99], v0 offset:17504
	s_waitcnt lgkmcnt(0)
	v_mfma_f32_32x32x16_bf16 v[64:79], v[96:99], v[92:95], v[64:79]
	ds_read_b128 v[96:99], v0 offset:22016
	s_waitcnt lgkmcnt(0)
	v_mfma_f32_32x32x16_bf16 v[48:63], v[96:99], v[80:83], v[48:63]
	ds_read_b128 v[96:99], v0 offset:22048
	s_waitcnt lgkmcnt(0)
	v_mfma_f32_32x32x16_bf16 v[48:63], v[96:99], v[84:87], v[48:63]
	ds_read_b128 v[96:99], v0 offset:22080
	s_waitcnt lgkmcnt(0)
	v_mfma_f32_32x32x16_bf16 v[48:63], v[96:99], v[88:91], v[48:63]
	ds_read_b128 v[96:99], v0 offset:22112
	s_waitcnt lgkmcnt(0)
	v_mfma_f32_32x32x16_bf16 v[48:63], v[96:99], v[92:95], v[48:63]
	ds_read_b128 v[96:99], v0 offset:26624
	s_waitcnt lgkmcnt(0)
	v_mfma_f32_32x32x16_bf16 v[32:47], v[96:99], v[80:83], v[32:47]
	ds_read_b128 v[96:99], v0 offset:26656
	s_waitcnt lgkmcnt(0)
	v_mfma_f32_32x32x16_bf16 v[32:47], v[96:99], v[84:87], v[32:47]
	ds_read_b128 v[96:99], v0 offset:26688
	s_waitcnt lgkmcnt(0)
	v_mfma_f32_32x32x16_bf16 v[32:47], v[96:99], v[88:91], v[32:47]
	ds_read_b128 v[96:99], v0 offset:26720
	s_waitcnt lgkmcnt(0)
	v_mfma_f32_32x32x16_bf16 v[32:47], v[96:99], v[92:95], v[32:47]
	ds_read_b128 v[96:99], v0 offset:31232
	s_waitcnt lgkmcnt(0)
	v_mfma_f32_32x32x16_bf16 v[16:31], v[96:99], v[80:83], v[16:31]
	ds_read_b128 v[80:83], v0 offset:31264
	s_waitcnt lgkmcnt(0)
	v_mfma_f32_32x32x16_bf16 v[16:31], v[80:83], v[84:87], v[16:31]
	ds_read_b128 v[80:83], v0 offset:31296
	s_waitcnt lgkmcnt(0)
	v_mfma_f32_32x32x16_bf16 v[16:31], v[80:83], v[88:91], v[16:31]
	ds_read_b128 v[80:83], v0 offset:31328
	s_waitcnt lgkmcnt(0)
	v_mfma_f32_32x32x16_bf16 v[16:31], v[80:83], v[92:95], v[16:31]
	s_setprio 0
	s_xor_b32 s4, s4, 1
	s_mul_i32 s5, s4, 0x8c00
	s_add_i32 s5, s5, 0
	v_add_u32_e32 v0, s5, v165
	s_waitcnt vmcnt(3)
	ds_write_b128 v0, v[6:9]
	v_add_u32_e32 v0, s5, v152
	s_waitcnt vmcnt(2)
	ds_write_b128 v0, v[2:5] offset:17408
	v_add_u32_e32 v0, s5, v166
	s_add_i32 s29, s29, -1
	s_waitcnt vmcnt(1)
	ds_write_b128 v0, v[144:147]
	v_add_u32_e32 v0, s5, v154
	v_lshl_add_u64 v[156:157], v[156:157], 0, s[68:69]
	v_lshl_add_u64 v[158:159], v[158:159], 0, s[68:69]
	v_lshl_add_u64 v[160:161], v[160:161], 0, s[80:81]
	s_cmp_eq_u32 s29, 0
	v_lshl_add_u64 v[162:163], v[162:163], 0, s[80:81]
	s_waitcnt vmcnt(0)
	ds_write_b128 v0, v[10:13] offset:17408
	s_cbranch_scc1 .LBB0_536
	v_mov_b32_e32 v155, v15
	s_branch .LBB0_532
; template <int HD, int MODE> ...
;     ...
;             f32x16 s0, s1;
; #pragma unroll
;             for (int r = 0; r < 16; ++r) { s0[r] = 0.f; s1[r] = 0.f; }
;             if constexpr (HD == 64) {
;                 bf16x8 kf0[HD / 16], kf1[HD / 16];
; #pragma unroll
;                 for (int d0 = 0; d0 < HD / 16; ++d0) { kf0[d0] = *(const LAS bf16x8*)(kb + d0 * 32); kf1[d0] = *(const LAS bf16x8*)(kb + 32 * KROW + d0 * 32); }
;                 __builtin_amdgcn_sched_barrier(0);
;                 __builtin_amdgcn_s_setprio(1);
; #pragma unroll
;                 for (int d0 = 0; d0 < HD / 16; ++d0) { s0 = __builtin_amdgcn_mfma_f32_32x32x16_bf16(kf0[d0], qf[d0], s0, 0, 0, 0); s1 = __builtin_amdgcn_mfma_f32_32x32x16_bf16(kf1[d0], qf[d0], s1, 0, 0, 0); }
;                 __builtin_amdgcn_s_setprio(0);
;             } else {
;             __builtin_amdgcn_s_setprio(1);
; #pragma unroll
;             for (int d0 = 0; d0 < HD / 16; ++d0) {
;                 const bf16x8 k0 = *(const LAS bf16x8*)(kb + d0 * 32);
;                 const bf16x8 k1 = *(const LAS bf16x8*)(kb + 32 * KROW + d0 * 32);
;                 s0 = __builtin_amdgcn_mfma_f32_32x32x16_bf16(k0, qf[d0], s0, 0, 0, 0);
;                 s1 = __builtin_amdgcn_mfma_f32_32x32x16_bf16(k1, qf[d0], s1, 0, 0, 0);
;             }
;             __builtin_amdgcn_s_setprio(0); }
;             if (MODE == 1) {
;                 const LAS float* bl = biasl + (64 * t + 8 * hi - (qlo + r32) + 384);
; #pragma unroll
;                 for (int r = 0; r < 16; ++r) { s0[r] += bl[16 * (r >> 3) + (r & 7)]; s1[r] += bl[32 + 16 * (r >> 3) + (r & 7)]; }
;             }
;             float mx = fmaxf(s0[0], s1[0]);
; #pragma unroll
;             for (int r = 1; r < 16; ++r) mx = fmaxf(mx, fmaxf(s0[r], s1[r]));
;             { auto rr = __builtin_amdgcn_permlane32_swap(__float_as_uint(mx), __float_as_uint(mx), false, false); mx = fmaxf(__uint_as_float(rr[0]), __uint_as_float(rr[1])); }
;             const float m_new = fmaxf(m_run, mx);
;             const bool grew = __any(m_new > m_run);
;             const float alpha = __builtin_amdgcn_exp2f(m_run - m_new);
;             m_run = m_new;
;             float rs = 0.f;
; #pragma unroll
;             for (int r = 0; r < 16; ++r) { s0[r] = __builtin_amdgcn_exp2f(s0[r] - m_new); s1[r] = __builtin_amdgcn_exp2f(s1[r] - m_new); rs += s0[r] + s1[r]; }
.LBB0_536:
	v_add3_u32 v0, s5, v167, v150
	s_waitcnt lgkmcnt(0)
	s_barrier
	s_setprio 1
	ds_read_b128 v[2:5], v0
	s_waitcnt lgkmcnt(0)
	v_mfma_f32_32x32x16_bf16 v[96:111], v[2:5], v[140:143], 0
	ds_read_b128 v[2:5], v0 offset:8704
	s_waitcnt lgkmcnt(0)
	v_mfma_f32_32x32x16_bf16 v[80:95], v[2:5], v[140:143], 0
	ds_read_b128 v[2:5], v0 offset:32
	s_waitcnt lgkmcnt(0)
	v_mfma_f32_32x32x16_bf16 v[96:111], v[2:5], v[136:139], v[96:111]
	ds_read_b128 v[2:5], v0 offset:8736
	s_waitcnt lgkmcnt(0)
	v_mfma_f32_32x32x16_bf16 v[80:95], v[2:5], v[136:139], v[80:95]
	ds_read_b128 v[2:5], v0 offset:64
	s_waitcnt lgkmcnt(0)
	v_mfma_f32_32x32x16_bf16 v[96:111], v[2:5], v[132:135], v[96:111]
	ds_read_b128 v[2:5], v0 offset:8768
	s_waitcnt lgkmcnt(0)
	v_mfma_f32_32x32x16_bf16 v[80:95], v[2:5], v[132:135], v[80:95]
	ds_read_b128 v[2:5], v0 offset:96
	s_waitcnt lgkmcnt(0)
	v_mfma_f32_32x32x16_bf16 v[96:111], v[2:5], v[128:131], v[96:111]
	ds_read_b128 v[2:5], v0 offset:8800
	s_waitcnt lgkmcnt(0)
	v_mfma_f32_32x32x16_bf16 v[80:95], v[2:5], v[128:131], v[80:95]
	ds_read_b128 v[2:5], v0 offset:128
	s_waitcnt lgkmcnt(0)
	v_mfma_f32_32x32x16_bf16 v[96:111], v[2:5], v[124:127], v[96:111]
	ds_read_b128 v[2:5], v0 offset:8832
	s_waitcnt lgkmcnt(0)
	v_mfma_f32_32x32x16_bf16 v[80:95], v[2:5], v[124:127], v[80:95]
	ds_read_b128 v[2:5], v0 offset:160
	s_waitcnt lgkmcnt(0)
	v_mfma_f32_32x32x16_bf16 v[96:111], v[2:5], v[120:123], v[96:111]
	ds_read_b128 v[2:5], v0 offset:8864
	s_waitcnt lgkmcnt(0)
	v_mfma_f32_32x32x16_bf16 v[80:95], v[2:5], v[120:123], v[80:95]
	ds_read_b128 v[2:5], v0 offset:192
	s_waitcnt lgkmcnt(0)
	v_mfma_f32_32x32x16_bf16 v[96:111], v[2:5], v[116:119], v[96:111]
	ds_read_b128 v[2:5], v0 offset:8896
	s_waitcnt lgkmcnt(0)
	v_mfma_f32_32x32x16_bf16 v[80:95], v[2:5], v[116:119], v[80:95]
	ds_read_b128 v[2:5], v0 offset:224
	s_waitcnt lgkmcnt(0)
	v_mfma_f32_32x32x16_bf16 v[96:111], v[2:5], v[112:115], v[96:111]
	ds_read_b128 v[2:5], v0 offset:8928
	s_waitcnt lgkmcnt(0)
	v_mfma_f32_32x32x16_bf16 v[80:95], v[2:5], v[112:115], v[80:95]
	s_setprio 0
	s_nop 10
	v_max_f32_e32 v0, v81, v81
	v_max_f32_e32 v2, v97, v97
	v_max_f32_e32 v0, v2, v0
	v_max_f32_e32 v2, v82, v82
	v_max_f32_e32 v3, v98, v98
	v_max_f32_e32 v2, v3, v2
	v_max_f32_e32 v3, v83, v83
	v_max_f32_e32 v4, v99, v99
	v_max3_f32 v0, v96, v80, v0
	v_max_f32_e32 v3, v4, v3
	v_max3_f32 v0, v0, v2, v3
	v_max_f32_e32 v2, v84, v84
	v_max_f32_e32 v3, v100, v100
	v_max_f32_e32 v2, v3, v2
	v_max_f32_e32 v3, v85, v85
	v_max_f32_e32 v4, v101, v101
	v_max_f32_e32 v3, v4, v3
	v_max3_f32 v0, v0, v2, v3
	v_max_f32_e32 v2, v86, v86
	v_max_f32_e32 v3, v102, v102
	v_max_f32_e32 v2, v3, v2
	v_max_f32_e32 v3, v87, v87
	v_max_f32_e32 v4, v103, v103
	v_max_f32_e32 v3, v4, v3
	v_max3_f32 v0, v0, v2, v3
	v_max_f32_e32 v2, v88, v88
	v_max_f32_e32 v3, v104, v104
	v_max_f32_e32 v2, v3, v2
	v_max_f32_e32 v3, v89, v89
	v_max_f32_e32 v4, v105, v105
	v_max_f32_e32 v3, v4, v3
	v_max3_f32 v0, v0, v2, v3
	v_max_f32_e32 v2, v90, v90
	v_max_f32_e32 v3, v106, v106
	v_max_f32_e32 v2, v3, v2
	v_max_f32_e32 v3, v91, v91
	v_max_f32_e32 v4, v107, v107
	v_max_f32_e32 v3, v4, v3
	v_max3_f32 v0, v0, v2, v3
	v_max_f32_e32 v2, v92, v92
	v_max_f32_e32 v3, v108, v108
	v_max_f32_e32 v2, v3, v2
	v_max_f32_e32 v3, v93, v93
	v_max_f32_e32 v4, v109, v109
	v_max_f32_e32 v3, v4, v3
	v_max3_f32 v0, v0, v2, v3
	v_max_f32_e32 v2, v94, v94
	v_max_f32_e32 v3, v110, v110
	v_max_f32_e32 v2, v3, v2
	v_max_f32_e32 v3, v95, v95
	v_max_f32_e32 v4, v111, v111
	v_max_f32_e32 v3, v4, v3
	v_max3_f32 v0, v0, v2, v3
	v_mov_b32_e32 v2, v0
	s_nop 1
	v_permlane32_swap_b32_e32 v0, v2
	v_max3_f32 v0, v153, v0, v2
	v_sub_f32_e32 v2, v153, v0
	v_exp_f32_e32 v2, v2
	v_cmp_gt_f32_e32 vcc, v0, v153
	s_cbranch_vccz .LBB0_530
	v_mul_f32_e32 v78, v78, v2
	v_mul_f32_e32 v79, v79, v2
	v_mul_f32_e32 v76, v76, v2
	v_mul_f32_e32 v77, v77, v2
	v_mul_f32_e32 v74, v74, v2
	v_mul_f32_e32 v75, v75, v2
	v_mul_f32_e32 v72, v72, v2
	v_mul_f32_e32 v73, v73, v2
	v_mul_f32_e32 v70, v70, v2
	v_mul_f32_e32 v71, v71, v2
	v_mul_f32_e32 v68, v68, v2
	v_mul_f32_e32 v69, v69, v2
	v_mul_f32_e32 v66, v66, v2
	v_mul_f32_e32 v67, v67, v2
	v_mul_f32_e32 v64, v64, v2
	v_mul_f32_e32 v65, v65, v2
	v_mul_f32_e32 v62, v62, v2
	v_mul_f32_e32 v63, v63, v2
	v_mul_f32_e32 v60, v60, v2
	v_mul_f32_e32 v61, v61, v2
	v_mul_f32_e32 v58, v58, v2
	v_mul_f32_e32 v59, v59, v2
	v_mul_f32_e32 v56, v56, v2
	v_mul_f32_e32 v57, v57, v2
	v_mul_f32_e32 v54, v54, v2
	v_mul_f32_e32 v55, v55, v2
	v_mul_f32_e32 v52, v52, v2
	v_mul_f32_e32 v53, v53, v2
	v_mul_f32_e32 v50, v50, v2
	v_mul_f32_e32 v51, v51, v2
	v_mul_f32_e32 v48, v48, v2
	v_mul_f32_e32 v49, v49, v2
	v_mul_f32_e32 v46, v46, v2
	v_mul_f32_e32 v47, v47, v2
	v_mul_f32_e32 v44, v44, v2
	v_mul_f32_e32 v45, v45, v2
	v_mul_f32_e32 v42, v42, v2
	v_mul_f32_e32 v43, v43, v2
	v_mul_f32_e32 v40, v40, v2
	v_mul_f32_e32 v41, v41, v2
	v_mul_f32_e32 v38, v38, v2
	v_mul_f32_e32 v39, v39, v2
	v_mul_f32_e32 v36, v36, v2
	v_mul_f32_e32 v37, v37, v2
	v_mul_f32_e32 v34, v34, v2
	v_mul_f32_e32 v35, v35, v2
	v_mul_f32_e32 v32, v32, v2
	v_mul_f32_e32 v33, v33, v2
	v_mul_f32_e32 v30, v30, v2
	v_mul_f32_e32 v31, v31, v2
	v_mul_f32_e32 v28, v28, v2
	v_mul_f32_e32 v29, v29, v2
	v_mul_f32_e32 v26, v26, v2
	v_mul_f32_e32 v27, v27, v2
	v_mul_f32_e32 v24, v24, v2
	v_mul_f32_e32 v25, v25, v2
	v_mul_f32_e32 v22, v22, v2
	v_mul_f32_e32 v23, v23, v2
	v_mul_f32_e32 v20, v20, v2
	v_mul_f32_e32 v21, v21, v2
	v_mul_f32_e32 v18, v18, v2
	v_mul_f32_e32 v19, v19, v2
	v_mul_f32_e32 v16, v16, v2
	v_mul_f32_e32 v17, v17, v2
	s_branch .LBB0_530
